# sample mixer phase: double-duty workgroups run their attention item first and the hgrn pass-2 item second
# speedup vs baseline: 1.0203x; 1.0035x over previous
.Lattn_static:
	s_waitcnt lgkmcnt(0)
	ds_read_b32 v2, v196 offset:4
	v_readlane_b32 s99, v255, 12
	s_waitcnt lgkmcnt(0)
	v_readfirstlane_b32 s24, v2
	s_nop 3
	s_and_b32 s25, s99, 7
	s_lshl_b32 s25, s25, 6
	s_lshr_b32 s26, s99, 3
	s_or_b32 s25, s25, s26
	s_add_i32 s25, s25, 0x100
	s_cmpk_lt_u32 s99, 0x100
	s_cselect_b32 s26, 0, 1
	s_add_i32 s26, s26, s24
	s_add_i32 s24, s24, 1
	s_cmp_eq_u32 s26, 1
	s_cselect_b32 s98, s25, 0x300
	s_cmp_eq_u32 s26, 0
	s_cselect_b32 s98, s99, s98
	s_sub_u32 vcc_lo, s24, 1
	s_cmpk_lt_u32 s99, 0x100
	s_cbranch_scc0 .Lattn_first_done
	s_cmp_eq_u32 vcc_lo, 0
	s_cselect_b32 s98, s25, 0x300
	s_cmp_eq_u32 vcc_lo, 1
	s_cselect_b32 s98, s99, s98
.Lattn_first_done:
	s_cmp_gt_u32 s26, 1
	s_cselect_b32 s24, 0, s24
	v_mov_b32_e32 v2, s24
	ds_write_b32 v196, v2 offset:4
	v_mov_b32_e32 v2, s98
